# NSA selected-block loop: union sel mask + next selected block K/V prefetched by LDS-DMA
# speedup vs baseline: 1.0596x; 1.0021x over previous
.LBB0_396:
	s_or_b32 s0, s80, 32
	s_lshl_b32 s1, s22, 18
	s_and_b32 s0, s0, 0xfe0
	s_add_i32 s48, s95, s1
	s_lshr_b32 s71, s80, 5
	s_add_i32 s0, s0, 32
	s_lshl_b64 s[76:77], s[48:49], 1
	v_lshlrev_b64 v[144:145], 4, v[138:139]
	s_add_u32 s6, s85, s76
	v_or_b32_e32 v32, v144, v132
	v_mov_b32_e32 v33, v145
	s_addc_u32 s7, s86, s77
	v_mov_b32_e32 v34, v133
	v_mov_b32_e32 v35, v133
	v_lshl_add_u64 v[138:139], s[6:7], 0, v[32:33]
	v_mov_b32_e32 v142, v133
	v_mov_b32_e32 v143, v133
	v_mov_b32_e32 v32, v133
	v_mov_b32_e32 v33, v133
	v_mov_b64_e32 v[50:51], v[34:35]
	v_mov_b64_e32 v[66:67], v[34:35]
	v_mov_b64_e32 v[82:83], v[34:35]
	v_mov_b64_e32 v[38:39], v[34:35]
	v_mov_b64_e32 v[54:55], v[34:35]
	v_mov_b64_e32 v[70:71], v[34:35]
	v_mov_b64_e32 v[86:87], v[34:35]
	v_mov_b64_e32 v[42:43], v[34:35]
	v_mov_b64_e32 v[58:59], v[34:35]
	v_mov_b64_e32 v[74:75], v[34:35]
	v_mov_b64_e32 v[90:91], v[34:35]
	v_mov_b64_e32 v[46:47], v[34:35]
	v_mov_b64_e32 v[62:63], v[34:35]
	v_mov_b64_e32 v[78:79], v[34:35]
	v_mov_b64_e32 v[94:95], v[34:35]
	v_sub_u32_e32 v131, v128, v130
	s_mov_b32 s1, 0
	v_mov_b64_e32 v[48:49], v[32:33]
	v_mov_b64_e32 v[64:65], v[32:33]
	v_mov_b64_e32 v[80:81], v[32:33]
	v_mov_b64_e32 v[36:37], v[32:33]
	v_mov_b64_e32 v[52:53], v[32:33]
	v_mov_b64_e32 v[68:69], v[32:33]
	v_mov_b64_e32 v[84:85], v[32:33]
	v_mov_b64_e32 v[40:41], v[32:33]
	v_mov_b64_e32 v[56:57], v[32:33]
	v_mov_b64_e32 v[72:73], v[32:33]
	v_mov_b64_e32 v[88:89], v[32:33]
	v_mov_b64_e32 v[44:45], v[32:33]
	v_mov_b64_e32 v[60:61], v[32:33]
	v_mov_b64_e32 v[76:77], v[32:33]
	v_mov_b64_e32 v[92:93], v[32:33]
	s_mov_b32 s26, 0
	v_mov_b64_e32 v[146:147], v[142:143]
	v_readlane_b32 s98, v140, 0
	v_readlane_b32 s99, v141, 0
	v_readlane_b32 s100, v140, 1
	v_readlane_b32 s101, v141, 1
	s_or_b32 s98, s98, s100
	s_or_b32 s99, s99, s101
	v_readlane_b32 s100, v140, 2
	v_readlane_b32 s101, v141, 2
	s_or_b32 s98, s98, s100
	s_or_b32 s99, s99, s101
	v_readlane_b32 s100, v140, 3
	v_readlane_b32 s101, v141, 3
	s_or_b32 s98, s98, s100
	s_or_b32 s99, s99, s101
	v_readlane_b32 s100, v140, 4
	v_readlane_b32 s101, v141, 4
	s_or_b32 s98, s98, s100
	s_or_b32 s99, s99, s101
	v_readlane_b32 s100, v140, 5
	v_readlane_b32 s101, v141, 5
	s_or_b32 s98, s98, s100
	s_or_b32 s99, s99, s101
	v_readlane_b32 s100, v140, 6
	v_readlane_b32 s101, v141, 6
	s_or_b32 s98, s98, s100
	s_or_b32 s99, s99, s101
	v_readlane_b32 s100, v140, 7
	v_readlane_b32 s101, v141, 7
	s_or_b32 s98, s98, s100
	s_or_b32 s99, s99, s101
	v_readlane_b32 s100, v140, 8
	v_readlane_b32 s101, v141, 8
	s_or_b32 s98, s98, s100
	s_or_b32 s99, s99, s101
	v_readlane_b32 s100, v140, 9
	v_readlane_b32 s101, v141, 9
	s_or_b32 s98, s98, s100
	s_or_b32 s99, s99, s101
	v_readlane_b32 s100, v140, 10
	v_readlane_b32 s101, v141, 10
	s_or_b32 s98, s98, s100
	s_or_b32 s99, s99, s101
	v_readlane_b32 s100, v140, 11
	v_readlane_b32 s101, v141, 11
	s_or_b32 s98, s98, s100
	s_or_b32 s99, s99, s101
	v_readlane_b32 s100, v140, 12
	v_readlane_b32 s101, v141, 12
	s_or_b32 s98, s98, s100
	s_or_b32 s99, s99, s101
	v_readlane_b32 s100, v140, 13
	v_readlane_b32 s101, v141, 13
	s_or_b32 s98, s98, s100
	s_or_b32 s99, s99, s101
	v_readlane_b32 s100, v140, 14
	v_readlane_b32 s101, v141, 14
	s_or_b32 s98, s98, s100
	s_or_b32 s99, s99, s101
	v_readlane_b32 s100, v140, 15
	v_readlane_b32 s101, v141, 15
	s_or_b32 s98, s98, s100
	s_or_b32 s99, s99, s101
	s_lshr_b32 s100, s0, 6
	s_sub_i32 s100, 64, s100
	s_mov_b64 s[10:11], -1
	s_lshr_b64 s[10:11], s[10:11], s100
	s_and_b64 s[98:99], s[98:99], s[10:11]
	v_lshl_add_u32 v252, v181, 4, s79
	v_add_co_u32_e32 v248, vcc, 0xfffff400, v138
	s_nop 1
	v_addc_co_u32_e32 v249, vcc, -1, v139, vcc
	v_add_co_u32_e32 v250, vcc, 0xff000000, v248
	s_nop 1
	v_addc_co_u32_e32 v251, vcc, -1, v249, vcc
	s_waitcnt vmcnt(0)
	s_add_i32 m0, s79, 0x1000
	s_nop 0
	global_load_lds_dwordx4 v[250:251], off
	global_load_lds_dwordx4 v[250:251], off offset:1024
	global_load_lds_dwordx4 v[250:251], off offset:2048
	global_load_lds_dwordx4 v[250:251], off offset:3072
	s_add_i32 m0, s79, 0x2000
	s_nop 0
	global_load_lds_dwordx4 v[248:249], off
	global_load_lds_dwordx4 v[248:249], off offset:1024
	global_load_lds_dwordx4 v[248:249], off offset:2048
	global_load_lds_dwordx4 v[248:249], off offset:3072
	s_branch .LBB0_398

.LBB0_398:
	s_lshr_b32 s8, s26, 1
	s_sub_i32 s9, s8, 32
	s_cmp_lt_u32 s26, 64
	s_cselect_b64 vcc, -1, 0
	s_and_b64 s[6:7], vcc, exec
	s_cselect_b32 s6, s8, s9
	v_cndmask_b32_e32 v96, v141, v140, vcc
	s_lshl_b32 s6, 1, s6
	v_and_b32_e32 v96, s6, v96
	v_cmp_ne_u32_e64 s[8:9], 0, v96
	s_mov_b64 vcc, s[8:9]
	s_cbranch_vccz .LBB0_397
	v_add_u32_e32 v152, s1, v130
	s_waitcnt vmcnt(0)
	ds_read_b128 v[124:127], v252 offset:4096
	ds_read_b128 v[120:123], v252 offset:5120
	ds_read_b128 v[116:119], v252 offset:6144
	ds_read_b128 v[112:115], v252 offset:7168
	ds_read_b128 v[108:111], v252 offset:8192
	ds_read_b128 v[104:107], v252 offset:9216
	ds_read_b128 v[100:103], v252 offset:10240
	ds_read_b128 v[96:99], v252 offset:11264
	s_add_i32 s10, s26, 1
	s_lshr_b32 s11, s26, 1
	s_add_i32 s11, s11, 1
	s_lshr_b64 s[12:13], s[98:99], s11
	s_ff1_i32_b64 s14, s[12:13]
	s_cmp_lt_i32 s14, 0
	s_cselect_b32 s14, 0, s14
	s_add_i32 s14, s14, s11
	s_lshl_b32 s14, s14, 1
	s_bitcmp1_b32 s26, 0
	s_cselect_b32 s10, s14, s10
	s_sub_i32 s10, s10, s26
	s_lshl_b32 s10, s10, 12
	s_add_i32 s10, s10, 0xfffff400
	v_add_co_u32_e32 v248, vcc, s10, v138
	s_nop 1
	v_addc_co_u32_e32 v249, vcc, 0, v139, vcc
	v_add_co_u32_e32 v250, vcc, 0xff000000, v248
	s_nop 1
	v_addc_co_u32_e32 v251, vcc, -1, v249, vcc
	v_add_u32_e32 v180, s80, v131
	v_add_u32_e32 v200, -1, v180
	v_add_u32_e32 v204, 2, v152
	v_add_u32_e32 v205, -2, v180
	v_add_u32_e32 v206, 3, v152
	v_cvt_f32_i32_e32 v223, v200
	v_cmp_le_i32_e64 s[12:13], v204, v134
	v_cvt_f32_i32_e32 v224, v205
	v_cmp_le_i32_e64 s[14:15], v206, v134
	v_cmp_le_i32_e32 vcc, v152, v134
	v_cvt_f32_i32_e32 v222, v180
	v_cmp_lt_i32_e64 s[6:7], v152, v134
	v_add_u32_e32 v208, -3, v180
	v_add_u32_e32 v209, 4, v152
	v_add_u32_e32 v210, -4, v180
	v_add_u32_e32 v211, 5, v152
	v_add_u32_e32 v212, -5, v180
	v_add_u32_e32 v213, 6, v152
	v_add_u32_e32 v214, -6, v180
	v_add_u32_e32 v152, 7, v152
	v_add_u32_e32 v180, -7, v180
	v_cvt_f32_i32_e32 v227, v212
	v_cvt_f32_i32_e32 v228, v214
	v_cmp_le_i32_e64 s[24:25], v152, v134
	v_cvt_f32_i32_e32 v152, v180
	v_cmp_le_i32_e64 s[16:17], v209, v134
	v_cmp_le_i32_e64 s[20:21], v211, v134
	v_cmp_le_i32_e64 s[22:23], v213, v134
	s_and_b64 s[18:19], s[8:9], vcc
	s_and_b64 s[10:11], s[8:9], s[6:7]
	s_and_b64 s[12:13], s[8:9], s[12:13]
	s_and_b64 s[14:15], s[8:9], s[14:15]
	s_and_b64 s[16:17], s[8:9], s[16:17]
	s_and_b64 vcc, s[8:9], s[20:21]
	s_and_b64 s[6:7], s[8:9], s[22:23]
	s_and_b64 s[8:9], s[24:25], s[8:9]
	v_cvt_f32_i32_e32 v225, v208
	v_cvt_f32_i32_e32 v226, v210
	s_waitcnt lgkmcnt(0)
	s_add_i32 m0, s79, 0x1000
	s_nop 0
	global_load_lds_dwordx4 v[250:251], off
	global_load_lds_dwordx4 v[250:251], off offset:1024
	global_load_lds_dwordx4 v[250:251], off offset:2048
	global_load_lds_dwordx4 v[250:251], off offset:3072
	s_add_i32 m0, s79, 0x2000
	s_nop 0
	global_load_lds_dwordx4 v[248:249], off
	global_load_lds_dwordx4 v[248:249], off offset:1024
	global_load_lds_dwordx4 v[248:249], off offset:2048
	global_load_lds_dwordx4 v[248:249], off offset:3072
	v_mfma_f32_16x16x32_bf16 v[196:199], v[124:127], v[0:3], 0
	v_mfma_f32_16x16x32_bf16 v[200:203], v[116:119], v[0:3], 0
	v_mfma_f32_16x16x32_bf16 v[204:207], v[124:127], v[8:11], 0
	v_mfma_f32_16x16x32_bf16 v[196:199], v[120:123], v[4:7], v[196:199]
	v_mfma_f32_16x16x32_bf16 v[200:203], v[112:115], v[4:7], v[200:203]
	v_mfma_f32_16x16x32_bf16 v[204:207], v[120:123], v[12:15], v[204:207]
	s_nop 4
	v_add_f32_e32 v180, 0xc1800000, v196
	v_add_f32_e32 v196, 0xc1800000, v197
	v_add_f32_e32 v197, 0xc1800000, v198
	v_add_f32_e32 v198, 0xc1800000, v199
	v_add_f32_e32 v199, 0xc1800000, v200
	v_add_f32_e32 v200, 0xc1800000, v201
	v_add_f32_e32 v201, 0xc1800000, v202
	v_add_f32_e32 v202, 0xc1800000, v203
	v_add_f32_e32 v203, 0xc1800000, v204
	v_fma_f32 v200, -v170, v227, v200
	v_fma_f32 v201, -v170, v228, v201
	v_fma_f32 v202, -v170, v152, v202
	v_fma_f32 v203, -v171, v222, v203
	v_exp_f32_e32 v200, v200
	v_exp_f32_e32 v201, v201
	v_exp_f32_e32 v202, v202
	v_exp_f32_e32 v203, v203
	v_add_f32_e32 v204, 0xc1800000, v205
	v_fma_f32 v204, -v171, v223, v204
	v_exp_f32_e32 v208, v204
	v_cndmask_b32_e32 v217, 0, v200, vcc
	v_cndmask_b32_e64 v219, 0, v201, s[6:7]
	v_cndmask_b32_e64 v221, 0, v202, s[8:9]
	v_cndmask_b32_e64 v204, 0, v203, s[18:19]
	v_mfma_f32_16x16x32_bf16 v[200:203], v[116:119], v[8:11], 0
	v_fma_f32 v180, -v170, v222, v180
	v_exp_f32_e32 v180, v180
	v_add_f32_e32 v206, 0xc1800000, v206
	v_mfma_f32_16x16x32_bf16 v[200:203], v[112:115], v[12:15], v[200:203]
	v_fma_f32 v196, -v170, v223, v196
	v_cndmask_b32_e64 v205, 0, v180, s[18:19]
	v_fma_f32 v180, -v171, v224, v206
	v_exp_f32_e32 v180, v180
	v_fma_f32 v197, -v170, v224, v197
	s_nop 2
	v_add_f32_e32 v200, 0xc1800000, v200
	v_fma_f32 v200, -v171, v226, v200
	v_exp_f32_e32 v200, v200
	v_cndmask_b32_e64 v210, 0, v180, s[12:13]
	v_add_f32_e32 v180, 0xc1800000, v201
	v_add_f32_e32 v201, 0xc1800000, v203
	v_cndmask_b32_e64 v214, 0, v200, s[16:17]
	v_add_f32_e32 v200, 0xc1800000, v202
	v_fma_f32 v200, -v171, v228, v200
	v_fma_f32 v201, -v171, v152, v201
	v_fma_f32 v198, -v170, v225, v198
	v_exp_f32_e32 v196, v196
	v_add_f32_e32 v206, 0xc1800000, v207
	v_exp_f32_e32 v200, v200
	v_exp_f32_e32 v201, v201
	v_fma_f32 v199, -v170, v226, v199
	v_exp_f32_e32 v197, v197
	v_exp_f32_e32 v198, v198
	v_fma_f32 v206, -v171, v225, v206
	v_exp_f32_e32 v199, v199
	v_exp_f32_e32 v206, v206
	v_fma_f32 v180, -v171, v227, v180
	v_exp_f32_e32 v180, v180
	v_cndmask_b32_e64 v209, 0, v196, s[10:11]
	v_cndmask_b32_e64 v208, 0, v208, s[10:11]
	v_cndmask_b32_e64 v218, 0, v200, s[6:7]
	v_cndmask_b32_e64 v220, 0, v201, s[8:9]
	v_pk_add_f32 v[200:201], v[204:205], 0 op_sel_hi:[1,0]
	v_cndmask_b32_e64 v211, 0, v197, s[12:13]
	v_cndmask_b32_e64 v213, 0, v198, s[14:15]
	v_cvt_pk_bf16_f32 v196, v205, v209
	v_cvt_pk_bf16_f32 v197, v211, v213
	v_pk_add_f32 v[200:201], v[208:209], v[200:201]
	v_cndmask_b32_e64 v215, 0, v199, s[16:17]
	v_cvt_pk_bf16_f32 v198, v215, v217
	v_cvt_pk_bf16_f32 v199, v219, v221
	v_cndmask_b32_e64 v212, 0, v206, s[14:15]
	v_mfma_f32_16x16x32_bf16 v[92:95], v[108:111], v[196:199], v[92:95]
	v_add_f32_e64 v200, v210, v200
	v_add_f32_e64 v201, v211, v201
	v_cndmask_b32_e32 v216, 0, v180, vcc
	v_mfma_f32_16x16x32_bf16 v[88:91], v[104:107], v[196:199], v[88:91]
	v_mfma_f32_16x16x32_bf16 v[84:87], v[100:103], v[196:199], v[84:87]
	v_mfma_f32_16x16x32_bf16 v[80:83], v[96:99], v[196:199], v[80:83]
	v_cvt_pk_bf16_f32 v196, v204, v208
	v_cvt_pk_bf16_f32 v197, v210, v212
	v_cvt_pk_bf16_f32 v198, v214, v216
	v_cvt_pk_bf16_f32 v199, v218, v220
	s_nop 0
	v_mfma_f32_16x16x32_bf16 v[76:79], v[108:111], v[196:199], v[76:79]
	v_mfma_f32_16x16x32_bf16 v[72:75], v[104:107], v[196:199], v[72:75]
	v_mfma_f32_16x16x32_bf16 v[68:71], v[100:103], v[196:199], v[68:71]
	v_mfma_f32_16x16x32_bf16 v[64:67], v[96:99], v[196:199], v[64:67]
	v_add_f32_e64 v196, v212, v200
	v_add_f32_e64 v197, v213, v201
	v_pk_add_f32 v[196:197], v[214:215], v[196:197]
	s_nop 0
	v_pk_add_f32 v[200:201], v[216:217], v[196:197]
	v_mfma_f32_16x16x32_bf16 v[196:199], v[124:127], v[16:19], 0
	v_add_f32_e64 v200, v218, v200
	v_add_f32_e64 v201, v219, v201
	v_pk_add_f32 v[200:201], v[220:221], v[200:201]
	v_mfma_f32_16x16x32_bf16 v[196:199], v[120:123], v[20:23], v[196:199]
	v_add_f32_e64 v146, v146, v200
	v_add_f32_e64 v147, v147, v201
	v_mfma_f32_16x16x32_bf16 v[200:203], v[116:119], v[16:19], 0
	v_mfma_f32_16x16x32_bf16 v[124:127], v[124:127], v[24:27], 0
	s_nop 3
	v_add_f32_e32 v180, 0xc1800000, v196
	v_add_f32_e32 v196, 0xc1800000, v197
	v_fma_f32 v196, -v172, v223, v196
	v_exp_f32_e32 v204, v196
	v_add_f32_e32 v196, 0xc1800000, v198
	v_mfma_f32_16x16x32_bf16 v[116:119], v[116:119], v[24:27], 0
	v_fma_f32 v196, -v172, v224, v196
	v_exp_f32_e32 v205, v196
	v_add_f32_e32 v196, 0xc1800000, v199
	v_fma_f32 v196, -v172, v225, v196
	v_exp_f32_e32 v206, v196
	v_mfma_f32_16x16x32_bf16 v[196:199], v[112:115], v[20:23], v[200:203]
	v_fma_f32 v180, -v172, v222, v180
	v_exp_f32_e32 v180, v180
	v_cndmask_b32_e64 v205, 0, v205, s[12:13]
	v_mfma_f32_16x16x32_bf16 v[120:123], v[120:123], v[28:31], v[124:127]
	v_cndmask_b32_e64 v203, 0, v204, s[10:11]
	s_nop 2
	v_add_f32_e32 v196, 0xc1800000, v196
	v_add_f32_e32 v197, 0xc1800000, v197
	v_mfma_f32_16x16x32_bf16 v[112:115], v[112:115], v[28:31], v[116:119]
	v_add_f32_e32 v198, 0xc1800000, v198
	v_add_f32_e32 v120, 0xc1800000, v120
	v_fma_f32 v120, -v173, v222, v120
	v_exp_f32_e32 v120, v120
	v_add_f32_e32 v199, 0xc1800000, v199
	s_nop 2
	v_add_f32_e32 v112, 0xc1800000, v112
	v_fma_f32 v112, -v173, v226, v112
	v_exp_f32_e32 v112, v112
	v_cndmask_b32_e64 v200, 0, v120, s[18:19]
	v_add_f32_e32 v120, 0xc1800000, v121
	v_add_f32_e32 v121, 0xc1800000, v122
	v_add_f32_e32 v122, 0xc1800000, v123
	v_cndmask_b32_e64 v208, 0, v112, s[16:17]
	v_add_f32_e32 v112, 0xc1800000, v113
	v_add_f32_e32 v113, 0xc1800000, v114
	v_add_f32_e32 v114, 0xc1800000, v115
	v_fma_f32 v196, -v172, v226, v196
	v_fma_f32 v197, -v172, v227, v197
	v_fma_f32 v198, -v172, v228, v198
	v_fma_f32 v199, -v172, v152, v199
	v_fma_f32 v120, -v173, v223, v120
	v_fma_f32 v121, -v173, v224, v121
	v_fma_f32 v122, -v173, v225, v122
	v_fma_f32 v112, -v173, v227, v112
	v_fma_f32 v113, -v173, v228, v113
	v_fma_f32 v114, -v173, v152, v114
	v_exp_f32_e32 v196, v196
	v_exp_f32_e32 v197, v197
	v_exp_f32_e32 v198, v198
	v_exp_f32_e32 v199, v199
	v_exp_f32_e32 v120, v120
	v_exp_f32_e32 v121, v121
	v_exp_f32_e32 v122, v122
	v_exp_f32_e32 v112, v112
	v_exp_f32_e32 v113, v113
	v_exp_f32_e32 v114, v114
	v_cndmask_b32_e64 v201, 0, v180, s[18:19]
	v_cndmask_b32_e64 v207, 0, v206, s[14:15]
	v_cndmask_b32_e64 v209, 0, v196, s[16:17]
	v_cndmask_b32_e32 v211, 0, v197, vcc
	v_cndmask_b32_e64 v213, 0, v198, s[6:7]
	v_cndmask_b32_e64 v215, 0, v199, s[8:9]
	v_cvt_pk_bf16_f32 v196, v201, v203
	v_cvt_pk_bf16_f32 v197, v205, v207
	v_cvt_pk_bf16_f32 v198, v209, v211
	v_cvt_pk_bf16_f32 v199, v213, v215
	v_cndmask_b32_e64 v202, 0, v120, s[10:11]
	v_cndmask_b32_e64 v204, 0, v121, s[12:13]
	v_cndmask_b32_e64 v206, 0, v122, s[14:15]
	v_mfma_f32_16x16x32_bf16 v[60:63], v[108:111], v[196:199], v[60:63]
	v_cndmask_b32_e32 v210, 0, v112, vcc
	v_cndmask_b32_e64 v212, 0, v113, s[6:7]
	v_cndmask_b32_e64 v214, 0, v114, s[8:9]
	v_cvt_pk_bf16_f32 v112, v200, v202
	v_cvt_pk_bf16_f32 v113, v204, v206
	v_cvt_pk_bf16_f32 v114, v208, v210
	v_cvt_pk_bf16_f32 v115, v212, v214
	v_mfma_f32_16x16x32_bf16 v[56:59], v[104:107], v[196:199], v[56:59]
	v_mfma_f32_16x16x32_bf16 v[44:47], v[108:111], v[112:115], v[44:47]
	v_add_f32_e64 v108, v200, 0
	v_add_f32_e64 v109, v201, 0
	v_pk_add_f32 v[108:109], v[202:203], v[108:109]
	v_mfma_f32_16x16x32_bf16 v[40:43], v[104:107], v[112:115], v[40:43]
	v_add_f32_e64 v108, v204, v108
	v_add_f32_e64 v109, v205, v109
	v_pk_add_f32 v[104:105], v[206:207], v[108:109]
	v_mfma_f32_16x16x32_bf16 v[52:55], v[100:103], v[196:199], v[52:55]
	v_add_f32_e64 v104, v208, v104
	v_add_f32_e64 v105, v209, v105
	v_pk_add_f32 v[104:105], v[210:211], v[104:105]
	v_mfma_f32_16x16x32_bf16 v[48:51], v[96:99], v[196:199], v[48:51]
	v_mfma_f32_16x16x32_bf16 v[36:39], v[100:103], v[112:115], v[36:39]
	v_add_f32_e64 v100, v212, v104
	v_add_f32_e64 v101, v213, v105
	v_pk_add_f32 v[100:101], v[214:215], v[100:101]
	v_mfma_f32_16x16x32_bf16 v[32:35], v[96:99], v[112:115], v[32:35]
	v_add_f32_e64 v142, v142, v100
	v_add_f32_e64 v143, v143, v101
	s_branch .LBB0_397
.LBB0_400:
	s_mov_b32 s75, s49
	v_lshl_add_u64 v[140:141], v[136:137], 0, s[74:75]
	s_mov_b32 s73, s49
	v_lshl_add_u64 v[136:137], v[136:137], 0, s[72:73]
	global_load_ushort v120, v[140:141], off offset:2562
	global_load_ushort v121, v[136:137], off offset:2562
	global_load_ushort v124, v[136:137], off offset:2568
	global_load_ushort v125, v[136:137], off offset:2574
	ds_bpermute_b32 v122, v167, v147
	ds_bpermute_b32 v123, v167, v146
	v_lshlrev_b32_e32 v100, 16, v129
	v_and_b32_e32 v101, 0xffff0000, v129
	v_lshlrev_b32_e32 v118, 16, v185
	s_waitcnt lgkmcnt(1)
	v_add_f32_e32 v122, v147, v122
	ds_bpermute_b32 v126, v166, v122
	s_waitcnt lgkmcnt(1)
	v_add_f32_e32 v123, v146, v123
	ds_bpermute_b32 v127, v166, v123
	v_and_b32_e32 v119, 0xffff0000, v185
	v_lshlrev_b32_e32 v96, 16, v189
	s_waitcnt lgkmcnt(1)
	v_add_f32_e32 v122, v122, v126
	v_and_b32_e32 v97, 0xffff0000, v189
	s_waitcnt lgkmcnt(0)
	v_add_f32_e32 v123, v123, v127
	v_lshlrev_b32_e32 v102, 16, v193
	v_and_b32_e32 v103, 0xffff0000, v193
	v_lshlrev_b32_e32 v106, 16, v195
	v_and_b32_e32 v107, 0xffff0000, v195
	v_lshlrev_b32_e32 v116, 16, v186
	v_and_b32_e32 v117, 0xffff0000, v186
	v_lshlrev_b32_e32 v112, 16, v188
	v_and_b32_e32 v113, 0xffff0000, v188
	v_lshlrev_b32_e32 v110, 16, v194
	v_and_b32_e32 v111, 0xffff0000, v194
	v_lshlrev_b32_e32 v108, 16, v192
	v_and_b32_e32 v109, 0xffff0000, v192
	v_lshlrev_b32_e32 v104, 16, v190
	v_and_b32_e32 v105, 0xffff0000, v190
	v_lshlrev_b32_e32 v114, 16, v187
	v_and_b32_e32 v115, 0xffff0000, v187
	v_lshlrev_b32_e32 v98, 16, v191
	v_and_b32_e32 v99, 0xffff0000, v191
	v_mov_b32_e32 v139, 0
	s_waitcnt vmcnt(3)
	v_lshlrev_b32_e32 v120, 16, v120
	v_mul_f32_e32 v120, 0xbfb8aa3b, v120
	v_exp_f32_e32 v120, v120
	s_waitcnt vmcnt(2)
	v_lshlrev_b32_e32 v121, 16, v121
	v_mul_f32_e32 v121, 0xbfb8aa3b, v121
	v_exp_f32_e32 v121, v121
	v_add_f32_e32 v120, 1.0, v120
	v_div_scale_f32 v126, s[0:1], v120, v120, 1.0
	v_rcp_f32_e32 v131, v126
	v_div_scale_f32 v127, vcc, 1.0, v120, 1.0
	v_add_f32_e32 v121, 1.0, v121
	v_fma_f32 v147, -v126, v131, 1.0
	v_fmac_f32_e32 v131, v147, v131
	v_mul_f32_e32 v147, v127, v131
	v_div_scale_f32 v129, s[0:1], v121, v121, 1.0
	v_fma_f32 v180, -v126, v147, v127
	v_rcp_f32_e32 v138, v129
	v_fmac_f32_e32 v147, v180, v131
	v_fma_f32 v126, -v126, v147, v127
	v_div_fmas_f32 v126, v126, v131, v147
	v_div_fixup_f32 v120, v126, v120, 1.0
	v_fma_f32 v152, -v129, v138, 1.0
	v_div_scale_f32 v126, s[0:1], v122, v122, v120
	v_div_scale_f32 v146, s[6:7], 1.0, v121, 1.0
	v_fmac_f32_e32 v138, v152, v138
	v_rcp_f32_e32 v127, v126
	v_mul_f32_e32 v152, v146, v138
	v_fma_f32 v185, -v129, v152, v146
	v_fmac_f32_e32 v152, v185, v138
	v_fma_f32 v129, -v129, v152, v146
	v_fma_f32 v146, -v126, v127, 1.0
	v_div_scale_f32 v131, vcc, v120, v122, v120
	v_fmac_f32_e32 v127, v146, v127
	v_mul_f32_e32 v146, v131, v127
	v_fma_f32 v147, -v126, v146, v131
	v_fmac_f32_e32 v146, v147, v127
	v_fma_f32 v126, -v126, v146, v131
	v_div_fmas_f32 v126, v126, v127, v146
	s_mov_b64 vcc, s[6:7]
	v_div_fixup_f32 v120, v126, v122, v120
	v_div_fmas_f32 v126, v129, v138, v152
	v_cmp_lt_f32_e32 vcc, 0, v122
	v_div_fixup_f32 v121, v126, v121, 1.0
	v_mov_b32_e32 v138, v139
	v_cndmask_b32_e32 v120, 0, v120, vcc
	v_pk_fma_f32 v[92:93], v[92:93], v[120:121], v[96:97] op_sel_hi:[1,0,1]
	v_pk_fma_f32 v[84:85], v[84:85], v[120:121], v[102:103] op_sel_hi:[1,0,1]
	v_div_scale_f32 v96, s[0:1], v123, v123, v121
	v_cvt_pk_bf16_f32 v204, v84, v85
	v_rcp_f32_e32 v84, v96
	v_pk_fma_f32 v[80:81], v[80:81], v[120:121], v[106:107] op_sel_hi:[1,0,1]
	v_div_scale_f32 v97, vcc, v121, v123, v121
	v_cvt_pk_bf16_f32 v203, v80, v81
	v_fma_f32 v80, -v96, v84, 1.0
	v_fmac_f32_e32 v84, v80, v84
	v_mul_f32_e32 v80, v97, v84
	v_fma_f32 v81, -v96, v80, v97
	v_fmac_f32_e32 v80, v81, v84
	v_fma_f32 v81, -v96, v80, v97
	v_div_fmas_f32 v80, v81, v84, v80
	v_div_fixup_f32 v80, v80, v123, v121
	v_cmp_lt_f32_e32 vcc, 0, v123
	v_pk_fma_f32 v[94:95], v[94:95], v[120:121], v[100:101] op_sel_hi:[1,0,1]
	v_pk_fma_f32 v[90:91], v[90:91], v[120:121], v[104:105] op_sel_hi:[1,0,1]
	v_cndmask_b32_e32 v80, 0, v80, vcc
	v_pk_fma_f32 v[74:75], v[74:75], v[80:81], v[118:119] op_sel_hi:[1,0,1]
	v_pk_fma_f32 v[72:73], v[72:73], v[80:81], v[116:117] op_sel_hi:[1,0,1]
	v_cvt_pk_bf16_f32 v198, v74, v75
	v_lshlrev_b32_e32 v74, 16, v178
	v_and_b32_e32 v75, 0xffff0000, v178
	v_pk_fma_f32 v[70:71], v[70:71], v[80:81], v[74:75] op_sel_hi:[1,0,1]
	v_cvt_pk_bf16_f32 v199, v72, v73
	v_lshlrev_b32_e32 v72, 16, v179
	v_cvt_pk_bf16_f32 v195, v70, v71
	s_waitcnt vmcnt(1)
	v_lshlrev_b32_e32 v70, 16, v124
	v_and_b32_e32 v73, 0xffff0000, v179
	v_mul_f32_e32 v70, 0xbfb8aa3b, v70
	v_pk_fma_f32 v[68:69], v[68:69], v[80:81], v[72:73] op_sel_hi:[1,0,1]
	v_exp_f32_e32 v72, v70
	ds_bpermute_b32 v71, v167, v143
	v_pk_fma_f32 v[76:77], v[76:77], v[80:81], v[112:113] op_sel_hi:[1,0,1]
	v_lshlrev_b32_e32 v70, 16, v177
	v_add_f32_e32 v72, 1.0, v72
	v_div_scale_f32 v75, s[0:1], v72, v72, 1.0
	v_cvt_pk_bf16_f32 v201, v76, v77
	s_waitcnt lgkmcnt(0)
	v_add_f32_e32 v73, v143, v71
	v_rcp_f32_e32 v76, v75
	ds_bpermute_b32 v74, v166, v73
	v_and_b32_e32 v71, 0xffff0000, v177
	v_pk_fma_f32 v[66:67], v[66:67], v[80:81], v[70:71] op_sel_hi:[1,0,1]
	v_fma_f32 v71, -v75, v76, 1.0
	v_fmac_f32_e32 v76, v71, v76
	v_div_scale_f32 v71, vcc, 1.0, v72, 1.0
	s_waitcnt lgkmcnt(0)
	v_add_f32_e32 v70, v73, v74
	v_mul_f32_e32 v73, v71, v76
	v_fma_f32 v74, -v75, v73, v71
	v_fmac_f32_e32 v73, v74, v76
	v_fma_f32 v71, -v75, v73, v71
	v_div_fmas_f32 v71, v71, v76, v73
	v_div_fixup_f32 v71, v71, v72, 1.0
	v_div_scale_f32 v72, s[0:1], v70, v70, v71
	v_rcp_f32_e32 v73, v72
	v_cvt_pk_bf16_f32 v196, v68, v69
	v_lshlrev_b32_e32 v68, 16, v184
	v_and_b32_e32 v69, 0xffff0000, v184
	v_pk_fma_f32 v[64:65], v[64:65], v[80:81], v[68:69] op_sel_hi:[1,0,1]
	v_cvt_pk_bf16_f32 v194, v66, v67
	v_lshlrev_b32_e32 v68, 16, v157
	v_cvt_pk_bf16_f32 v197, v64, v65
	v_fma_f32 v64, -v72, v73, 1.0
	v_fmac_f32_e32 v73, v64, v73
	v_div_scale_f32 v64, vcc, v71, v70, v71
	v_mul_f32_e32 v65, v64, v73
	v_fma_f32 v66, -v72, v65, v64
	v_fmac_f32_e32 v65, v66, v73
	v_fma_f32 v64, -v72, v65, v64
	v_div_fmas_f32 v64, v64, v73, v65
	v_div_fixup_f32 v64, v64, v70, v71
	v_cmp_lt_f32_e32 vcc, 0, v70
	v_and_b32_e32 v69, 0xffff0000, v157
	v_lshlrev_b32_e32 v66, 16, v158
	v_cndmask_b32_e32 v64, 0, v64, vcc
	v_pk_fma_f32 v[62:63], v[62:63], v[64:65], v[68:69] op_sel_hi:[1,0,1]
	v_and_b32_e32 v67, 0xffff0000, v158
	v_cvt_pk_bf16_f32 v192, v62, v63
	v_lshlrev_b32_e32 v62, 16, v159
	v_and_b32_e32 v63, 0xffff0000, v159
	v_pk_fma_f32 v[58:59], v[58:59], v[64:65], v[62:63] op_sel_hi:[1,0,1]
	v_pk_fma_f32 v[60:61], v[60:61], v[64:65], v[66:67] op_sel_hi:[1,0,1]
	v_cvt_pk_bf16_f32 v190, v58, v59
	v_lshlrev_b32_e32 v58, 16, v161
	v_and_b32_e32 v59, 0xffff0000, v161
	v_cvt_pk_bf16_f32 v193, v60, v61
	v_lshlrev_b32_e32 v60, 16, v160
	v_and_b32_e32 v61, 0xffff0000, v160
	v_pk_fma_f32 v[54:55], v[54:55], v[64:65], v[58:59] op_sel_hi:[1,0,1]
	v_pk_fma_f32 v[56:57], v[56:57], v[64:65], v[60:61] op_sel_hi:[1,0,1]
	v_cvt_pk_bf16_f32 v187, v54, v55
	s_waitcnt vmcnt(0)
	v_lshlrev_b32_e32 v54, 16, v125
	v_cvt_pk_bf16_f32 v191, v56, v57
	v_lshlrev_b32_e32 v56, 16, v174
	v_and_b32_e32 v57, 0xffff0000, v174
	v_mul_f32_e32 v54, 0xbfb8aa3b, v54
	v_pk_fma_f32 v[52:53], v[52:53], v[64:65], v[56:57] op_sel_hi:[1,0,1]
	v_exp_f32_e32 v56, v54
	ds_bpermute_b32 v55, v167, v142
	v_lshlrev_b32_e32 v54, 16, v175
	v_cvt_pk_bf16_f32 v188, v52, v53
	v_add_f32_e32 v56, 1.0, v56
	v_div_scale_f32 v59, s[0:1], v56, v56, 1.0
	s_waitcnt lgkmcnt(0)
	v_add_f32_e32 v57, v142, v55
	v_rcp_f32_e32 v60, v59
	ds_bpermute_b32 v58, v166, v57
	v_and_b32_e32 v55, 0xffff0000, v175
	v_pk_fma_f32 v[50:51], v[50:51], v[64:65], v[54:55] op_sel_hi:[1,0,1]
	v_fma_f32 v55, -v59, v60, 1.0
	v_fmac_f32_e32 v60, v55, v60
	v_div_scale_f32 v55, vcc, 1.0, v56, 1.0
	s_waitcnt lgkmcnt(0)
	v_add_f32_e32 v54, v57, v58
	v_mul_f32_e32 v57, v55, v60
	v_fma_f32 v58, -v59, v57, v55
	v_fmac_f32_e32 v57, v58, v60
	v_fma_f32 v55, -v59, v57, v55
	v_div_fmas_f32 v55, v55, v60, v57
	v_div_fixup_f32 v55, v55, v56, 1.0
	v_div_scale_f32 v56, s[0:1], v54, v54, v55
	v_rcp_f32_e32 v57, v56
	v_lshlrev_b32_e32 v52, 16, v176
	v_and_b32_e32 v53, 0xffff0000, v176
	v_pk_fma_f32 v[48:49], v[48:49], v[64:65], v[52:53] op_sel_hi:[1,0,1]
	v_cvt_pk_bf16_f32 v186, v50, v51
	v_and_b32_e32 v51, 0xffff0000, v155
	v_cvt_pk_bf16_f32 v189, v48, v49
	v_fma_f32 v48, -v56, v57, 1.0
	v_fmac_f32_e32 v57, v48, v57
	v_div_scale_f32 v48, vcc, v55, v54, v55
	v_mul_f32_e32 v49, v48, v57
	v_fma_f32 v50, -v56, v49, v48
	v_fmac_f32_e32 v49, v50, v57
	v_fma_f32 v48, -v56, v49, v48
	v_div_fmas_f32 v48, v48, v57, v49
	v_div_fixup_f32 v48, v48, v54, v55
	v_cmp_lt_f32_e32 vcc, 0, v54
	v_lshlrev_b32_e32 v50, 16, v155
	v_lshlrev_b32_e32 v52, 16, v156
	v_cndmask_b32_e32 v48, 0, v48, vcc
	v_and_b32_e32 v53, 0xffff0000, v156
	v_pk_fma_f32 v[46:47], v[46:47], v[48:49], v[52:53] op_sel_hi:[1,0,1]
	v_pk_fma_f32 v[44:45], v[44:45], v[48:49], v[50:51] op_sel_hi:[1,0,1]
	v_cvt_pk_bf16_f32 v185, v46, v47
	v_lshlrev_b32_e32 v46, 16, v154
	v_cvt_pk_bf16_f32 v184, v44, v45
	v_lshlrev_b32_e32 v44, 16, v153
	v_and_b32_e32 v45, 0xffff0000, v153
	v_and_b32_e32 v47, 0xffff0000, v154
	v_pk_fma_f32 v[42:43], v[42:43], v[48:49], v[46:47] op_sel_hi:[1,0,1]
	v_pk_fma_f32 v[40:41], v[40:41], v[48:49], v[44:45] op_sel_hi:[1,0,1]
	v_cvt_pk_bf16_f32 v179, v42, v43
	v_lshlrev_b32_e32 v42, 16, v151
	v_cvt_pk_bf16_f32 v178, v40, v41
	v_lshlrev_b32_e32 v40, 16, v150
	v_and_b32_e32 v41, 0xffff0000, v150
	v_and_b32_e32 v43, 0xffff0000, v151
	s_add_i32 s0, s80, 0xfffffe01
	v_pk_fma_f32 v[38:39], v[38:39], v[48:49], v[42:43] op_sel_hi:[1,0,1]
	v_pk_fma_f32 v[36:37], v[36:37], v[48:49], v[40:41] op_sel_hi:[1,0,1]
	s_lshr_b32 s0, s0, 5
	v_cvt_pk_bf16_f32 v176, v36, v37
	v_cvt_pk_bf16_f32 v177, v38, v39
	v_lshlrev_b32_e32 v36, 16, v148
	v_and_b32_e32 v37, 0xffff0000, v148
	v_lshlrev_b32_e32 v38, 16, v149
	v_and_b32_e32 v39, 0xffff0000, v149
	s_cmpk_gt_u32 s80, 0x1ff
	v_pk_fma_f32 v[88:89], v[88:89], v[120:121], v[98:99] op_sel_hi:[1,0,1]
	v_pk_fma_f32 v[86:87], v[86:87], v[120:121], v[108:109] op_sel_hi:[1,0,1]
	v_pk_fma_f32 v[82:83], v[82:83], v[120:121], v[110:111] op_sel_hi:[1,0,1]
	v_pk_fma_f32 v[78:79], v[78:79], v[80:81], v[114:115] op_sel_hi:[1,0,1]
	v_pk_fma_f32 v[34:35], v[34:35], v[48:49], v[38:39] op_sel_hi:[1,0,1]
	v_pk_fma_f32 v[32:33], v[32:33], v[48:49], v[36:37] op_sel_hi:[1,0,1]
	s_cselect_b32 s48, s0, 0
	v_cvt_pk_bf16_f32 v209, v92, v93
	v_cvt_pk_bf16_f32 v208, v94, v95
	v_cvt_pk_bf16_f32 v207, v88, v89
	v_cvt_pk_bf16_f32 v206, v90, v91
	v_cvt_pk_bf16_f32 v205, v86, v87
	v_cvt_pk_bf16_f32 v202, v82, v83
	v_cvt_pk_bf16_f32 v200, v78, v79
	v_cvt_pk_bf16_f32 v175, v32, v33
	v_cvt_pk_bf16_f32 v174, v34, v35
	s_cmp_gt_u32 s48, s71
	v_mov_b32_e32 v143, v139
	v_mov_b32_e32 v142, v139
	v_mov_b32_e32 v83, v139
	v_mov_b32_e32 v82, v139
	v_mov_b32_e32 v81, v139
	v_mov_b32_e32 v80, v139
	v_mov_b32_e32 v67, v139
	v_mov_b32_e32 v66, v139
	v_mov_b32_e32 v65, v139
	v_mov_b32_e32 v64, v139
	v_mov_b32_e32 v51, v139
	v_mov_b32_e32 v50, v139
	v_mov_b32_e32 v49, v139
	v_mov_b32_e32 v48, v139
	v_mov_b32_e32 v35, v139
	v_mov_b32_e32 v34, v139
	v_mov_b32_e32 v33, v139
	v_mov_b32_e32 v32, v139
	v_mov_b32_e32 v87, v139
	v_mov_b32_e32 v86, v139
	v_mov_b32_e32 v85, v139
	v_mov_b32_e32 v84, v139
	v_mov_b32_e32 v71, v139
	v_mov_b32_e32 v70, v139
	v_mov_b32_e32 v69, v139
	v_mov_b32_e32 v68, v139
	v_mov_b32_e32 v55, v139
	v_mov_b32_e32 v54, v139
	v_mov_b32_e32 v53, v139
	v_mov_b32_e32 v52, v139
	v_mov_b32_e32 v39, v139
	v_mov_b32_e32 v38, v139
	v_mov_b32_e32 v37, v139
	v_mov_b32_e32 v36, v139
	v_mov_b32_e32 v91, v139
	v_mov_b32_e32 v90, v139
	v_mov_b32_e32 v89, v139
	v_mov_b32_e32 v88, v139
	v_mov_b32_e32 v75, v139
	v_mov_b32_e32 v74, v139
	v_mov_b32_e32 v73, v139
	v_mov_b32_e32 v72, v139
	v_mov_b32_e32 v59, v139
	v_mov_b32_e32 v58, v139
	v_mov_b32_e32 v57, v139
	v_mov_b32_e32 v56, v139
	v_mov_b32_e32 v47, v139
	v_mov_b32_e32 v46, v139
	v_mov_b32_e32 v45, v139
	v_mov_b32_e32 v44, v139
	v_mov_b32_e32 v95, v139
	v_mov_b32_e32 v94, v139
	v_mov_b32_e32 v93, v139
	v_mov_b32_e32 v92, v139
	v_mov_b32_e32 v79, v139
	v_mov_b32_e32 v78, v139
	v_mov_b32_e32 v77, v139
	v_mov_b32_e32 v76, v139
	v_mov_b32_e32 v63, v139
	v_mov_b32_e32 v62, v139
	v_mov_b32_e32 v61, v139
	v_mov_b32_e32 v60, v139
	v_mov_b32_e32 v43, v139
	v_mov_b32_e32 v42, v139
	v_mov_b32_e32 v41, v139
	v_mov_b32_e32 v40, v139
	s_cbranch_scc1 .LBB0_369
	v_add3_u32 v32, s80, -7, v128
	s_add_i32 s0, s48, -1
	v_sub_u32_e32 v32, v32, v130
	s_lshl_b32 s1, s48, 5
	s_lshl_b64 s[6:7], s[48:49], 12
	v_subrev_u32_e32 v210, s1, v32
	v_lshl_add_u64 v[32:33], s[6:7], 0, v[144:145]
	s_add_u32 s6, s87, s76
	v_lshl_add_u64 v[32:33], v[32:33], 0, v[132:133]
	s_addc_u32 s7, s88, s77
	v_mov_b32_e32 v40, 0
	v_add3_u32 v211, v130, s1, 7
	v_lshl_add_u64 v[144:145], s[6:7], 0, v[32:33]
	s_waitcnt vmcnt(0)
	v_lshl_add_u32 v252, v181, 4, s79
	s_add_i32 s98, s79, 0x1000
	s_add_i32 s99, s79, 0x2000
	v_add_co_u32_e32 v250, vcc, 0xfefff400, v144
	s_nop 1
	v_addc_co_u32_e32 v251, vcc, -1, v145, vcc
	v_add_co_u32_e32 v248, vcc, 0xfffff400, v144
	s_nop 1
	v_addc_co_u32_e32 v249, vcc, -1, v145, vcc
	s_mov_b32 m0, s98
	s_nop 0
	global_load_lds_dwordx4 v[250:251], off
	global_load_lds_dwordx4 v[250:251], off offset:1024
	global_load_lds_dwordx4 v[250:251], off offset:2048
	global_load_lds_dwordx4 v[250:251], off offset:3072
	s_mov_b32 m0, s99
	s_nop 0
	global_load_lds_dwordx4 v[248:249], off
	global_load_lds_dwordx4 v[248:249], off offset:1024
	global_load_lds_dwordx4 v[248:249], off offset:2048
	global_load_lds_dwordx4 v[248:249], off offset:3072
	v_mov_b32_e32 v41, v40
	v_mov_b32_e32 v42, v40
	v_mov_b32_e32 v43, v40
	v_mov_b32_e32 v44, v40
	v_mov_b32_e32 v45, v40
	v_mov_b32_e32 v46, v40
	v_mov_b32_e32 v47, v40
	v_mov_b32_e32 v36, v40
	v_mov_b32_e32 v37, v40
	v_mov_b32_e32 v38, v40
	v_mov_b32_e32 v39, v40
	v_mov_b32_e32 v32, v40
	v_mov_b32_e32 v33, v40
	v_mov_b32_e32 v34, v40
	v_mov_b32_e32 v35, v40
	v_mov_b32_e32 v60, v40
	v_mov_b32_e32 v61, v40
	v_mov_b32_e32 v62, v40
	v_mov_b32_e32 v63, v40
	v_mov_b32_e32 v56, v40
	v_mov_b32_e32 v57, v40
	v_mov_b32_e32 v58, v40
	v_mov_b32_e32 v59, v40
	v_mov_b32_e32 v52, v40
	v_mov_b32_e32 v53, v40
	v_mov_b32_e32 v54, v40
	v_mov_b32_e32 v55, v40
	v_mov_b32_e32 v48, v40
	v_mov_b32_e32 v49, v40
	v_mov_b32_e32 v50, v40
	v_mov_b32_e32 v51, v40
	v_mov_b32_e32 v76, v40
	v_mov_b32_e32 v77, v40
	v_mov_b32_e32 v78, v40
	v_mov_b32_e32 v79, v40
	v_mov_b32_e32 v72, v40
	v_mov_b32_e32 v73, v40
	v_mov_b32_e32 v74, v40
	v_mov_b32_e32 v75, v40
	v_mov_b32_e32 v68, v40
	v_mov_b32_e32 v69, v40
	v_mov_b32_e32 v70, v40
	v_mov_b32_e32 v71, v40
	v_mov_b32_e32 v64, v40
	v_mov_b32_e32 v65, v40
	v_mov_b32_e32 v66, v40
	v_mov_b32_e32 v67, v40
	v_mov_b32_e32 v92, v40
	v_mov_b32_e32 v93, v40
	v_mov_b32_e32 v94, v40
	v_mov_b32_e32 v95, v40
	v_mov_b32_e32 v88, v40
	v_mov_b32_e32 v89, v40
	v_mov_b32_e32 v90, v40
	v_mov_b32_e32 v91, v40
	v_mov_b32_e32 v84, v40
	v_mov_b32_e32 v85, v40
	v_mov_b32_e32 v86, v40
	v_mov_b32_e32 v87, v40
	v_mov_b32_e32 v80, v40
	v_mov_b32_e32 v81, v40
	v_mov_b32_e32 v82, v40
	v_mov_b32_e32 v83, v40
	v_mov_b32_e32 v142, v40
	v_mov_b32_e32 v143, v40
	v_mov_b32_e32 v138, v40
	v_mov_b32_e32 v139, v40

	.amdhsa_kernel _Z10fwd_kernel7KParams
		.amdhsa_group_segment_fixed_size 0
		.amdhsa_private_segment_fixed_size 0
		.amdhsa_kernarg_size 472
		.amdhsa_user_sgpr_count 2
		.amdhsa_user_sgpr_dispatch_ptr 0
		.amdhsa_user_sgpr_queue_ptr 0
		.amdhsa_user_sgpr_kernarg_segment_ptr 1
		.amdhsa_user_sgpr_dispatch_id 0
		.amdhsa_user_sgpr_kernarg_preload_length 0
		.amdhsa_user_sgpr_kernarg_preload_offset 0
		.amdhsa_user_sgpr_private_segment_size 0
		.amdhsa_uses_dynamic_stack 0
		.amdhsa_enable_private_segment 0
		.amdhsa_system_sgpr_workgroup_id_x 1
		.amdhsa_system_sgpr_workgroup_id_y 0
		.amdhsa_system_sgpr_workgroup_id_z 0
		.amdhsa_system_sgpr_workgroup_info 0
		.amdhsa_system_vgpr_workitem_id 2
		.amdhsa_next_free_vgpr 256
		.amdhsa_next_free_sgpr 102
		.amdhsa_accum_offset 256
		.amdhsa_reserve_vcc 1
		.amdhsa_float_round_mode_32 0
		.amdhsa_float_round_mode_16_64 0
		.amdhsa_float_denorm_mode_32 3
		.amdhsa_float_denorm_mode_16_64 3
		.amdhsa_dx10_clamp 1
		.amdhsa_ieee_mode 1
		.amdhsa_fp16_overflow 0
		.amdhsa_tg_split 0
		.amdhsa_exception_fp_ieee_invalid_op 0
		.amdhsa_exception_fp_denorm_src 0
		.amdhsa_exception_fp_ieee_div_zero 0
		.amdhsa_exception_fp_ieee_overflow 0
		.amdhsa_exception_fp_ieee_underflow 0
		.amdhsa_exception_fp_ieee_inexact 0
		.amdhsa_exception_int_div_zero 0
	.end_amdhsa_kernel
